# attnvw + G3 epilogue stores 1..7 in saddr form (SGPR base + one running 32-bit VGPR offset) replacing v_mad_i64_i32 + v_lshl_add_u64 per store
# speedup vs baseline: 1.0011x; 1.0011x over previous
; __device__ __forceinline__ float ss2f(unsigned long long v) { return (float)v * (1.0f / 16777216.0f); }
; __device__ __forceinline__ f32x4 silu4(f32x4 v) { return (f32x4){silu1(v[0]), silu1(v[1]), silu1(v[2]), silu1(v[3])}; }
; __device__ __forceinline__ u32x4 pack8(f32x4 v0, f32x4 v1) { u32x4 w; w.x = cvt_pk_bf16(v0[0], v0[1]); w.y = cvt_pk_bf16(v0[2], v0[3]); w.z = cvt_pk_bf16(v1[0], v1[1]); w.w = cvt_pk_bf16(v1[2], v1[3]); return w; }
; __device__ __forceinline__ void rstd8(float (&r)[8], const PreSS& p, int fr) {
;     const float a = __builtin_amdgcn_rsqf(ss2f(p.v0) * (1.0f / 1024.0f) + RMS_EPS), b = __builtin_amdgcn_rsqf(ss2f(p.v1) * (1.0f / 1024.0f) + RMS_EPS);
; #pragma unroll
;     for (int k = 0; k < 8; ++k) r[k] = __shfl((k & 1) ? b : a, fr + 16 * (k >> 1));
; }
;     __device__ __forceinline__ void operator()(const f32x4 (&acc)[2][2][4][2], const Unit& u, int wr, int wc, int fr, int fq, const Pre& pre) const {
;         const int row0 = u.pm * BM + wr * 64 + fr, col0 = u.pn * HALF + wc * 32 + 8 * fq;
;         float rs8[8]; rstd8(rs8, pre, fr);
; #pragma unroll
;         for (int ai = 0; ai < 2; ++ai)
; #pragma unroll
;             for (int m = 0; m < 4; ++m) { const int row = row0 + ai * HALF + m * 16; const float r = rs8[ai * 4 + m];
;                 const f32x4 g0 = silu4(acc[ai][0][m][0] * r), g1 = silu4(acc[ai][0][m][1] * r);
;                 const f32x4 v0 = g0 * (acc[ai][1][m][0] * r), v1 = g1 * (acc[ai][1][m][1] * r);
;                 *(u32x4*)(O + (size_t)row * 2816 + col0) = pack8(v0, v1); }
.LBB0_155:
	s_waitcnt vmcnt(8)
	v_ffbh_u32_e32 v143, v153
	v_min_u32_e32 v143, 32, v143
	v_lshlrev_b64 v[152:153], v143, v[152:153]
	v_min_u32_e32 v152, 1, v152
	v_or_b32_e32 v152, v153, v152
	v_cvt_f32_u32_e32 v152, v152
	v_sub_u32_e32 v143, 32, v143
	v_lshl_or_b32 v164, s4, 7, v159
	v_ashrrev_i32_e32 v165, 31, v164
	v_ldexp_f32 v143, v152, v143
	v_ffbh_u32_e32 v152, v147
	v_min_u32_e32 v152, 32, v152
	v_lshlrev_b64 v[146:147], v152, v[146:147]
	v_min_u32_e32 v146, 1, v146
	v_or_b32_e32 v146, v147, v146
	v_mul_f32_e32 v143, 0x33800000, v143
	v_cvt_f32_u32_e32 v146, v146
	v_fmamk_f32 v143, v143, 0x3a800000, v233
	v_rsq_f32_e32 v143, v143
	v_sub_u32_e32 v147, 32, v152
	v_ldexp_f32 v146, v146, v147
	v_and_or_b32 v147, v236, 64, v145
	v_lshlrev_b32_e32 v147, 2, v147
	ds_bpermute_b32 v166, v147, v143
	ds_bpermute_b32 v160, v147, v143 offset:64
	ds_bpermute_b32 v156, v147, v143 offset:128
	ds_bpermute_b32 v152, v147, v143 offset:192
	v_mul_f32_e32 v146, 0x33800000, v146
	s_waitcnt lgkmcnt(3)
	v_mul_f32_e32 v196, 0xbfb8aa3b, v166
	v_mul_f32_e32 v197, 0xbf317218, v166
	v_pk_mul_f32 v[124:125], v[124:125], v[196:197] op_sel_hi:[1,0]
	v_pk_mul_f32 v[126:127], v[126:127], v[196:197] op_sel_hi:[1,0]
	v_exp_f32_e32 v143, v124
	v_pk_mul_f32 v[120:121], v[120:121], v[196:197] op_sel_hi:[1,0]
	v_pk_mul_f32 v[122:123], v[122:123], v[196:197] op_sel_hi:[1,0]
	v_fmamk_f32 v146, v146, 0x3a800000, v233
	v_add_f32_e32 v143, 1.0, v143
	v_rcp_f32_e32 v168, v143
	v_exp_f32_e32 v143, v125
	v_rsq_f32_e32 v146, v146
	v_pk_mul_f32 v[116:117], v[116:117], v[196:197] op_sel:[0,1]
	v_pk_mul_f32 v[118:119], v[118:119], v[196:197] op_sel:[0,1]
	v_add_f32_e32 v143, 1.0, v143
	v_rcp_f32_e32 v169, v143
	v_exp_f32_e32 v143, v126
	ds_bpermute_b32 v162, v147, v146
	v_pk_mul_f32 v[124:125], v[124:125], v[168:169]
	v_pk_mul_f32 v[112:113], v[112:113], v[196:197] op_sel:[0,1]
	v_add_f32_e32 v143, 1.0, v143
	v_rcp_f32_e32 v170, v143
	v_exp_f32_e32 v143, v127
	v_pk_mul_f32 v[116:117], v[116:117], v[124:125]
	v_pk_mul_f32 v[114:115], v[114:115], v[196:197] op_sel:[0,1]
	v_cvt_pk_bf16_f32 v116, v116, v117
	v_add_f32_e32 v143, 1.0, v143
	v_rcp_f32_e32 v171, v143
	v_exp_f32_e32 v143, v120
	s_movk_i32 s4, 0x1600
	v_pk_mul_f32 v[126:127], v[126:127], v[170:171]
	s_waitcnt lgkmcnt(0)
	v_mul_f32_e32 v234, 0xbfb8aa3b, v162
	v_mul_f32_e32 v235, 0xbf317218, v162
	v_pk_mul_f32 v[110:111], v[110:111], v[234:235] op_sel_hi:[1,0]
	v_add_f32_e32 v143, 1.0, v143
	v_rcp_f32_e32 v168, v143
	v_exp_f32_e32 v143, v121
	v_pk_mul_f32 v[118:119], v[118:119], v[126:127]
	v_pk_mul_f32 v[108:109], v[108:109], v[234:235] op_sel_hi:[1,0]
	v_cvt_pk_bf16_f32 v117, v118, v119
	v_add_f32_e32 v143, 1.0, v143
	v_rcp_f32_e32 v169, v143
	v_exp_f32_e32 v143, v122
	v_pk_mul_f32 v[106:107], v[106:107], v[234:235] op_sel_hi:[1,0]
	v_pk_mul_f32 v[120:121], v[120:121], v[168:169]
	v_pk_mul_f32 v[104:105], v[104:105], v[234:235] op_sel_hi:[1,0]
	v_add_f32_e32 v143, 1.0, v143
	v_rcp_f32_e32 v170, v143
	v_exp_f32_e32 v143, v123
	v_pk_mul_f32 v[112:113], v[112:113], v[120:121]
	v_pk_mul_f32 v[100:101], v[100:101], v[234:235] op_sel:[0,1]
	v_cvt_pk_bf16_f32 v118, v112, v113
	v_add_f32_e32 v143, 1.0, v143
	v_rcp_f32_e32 v171, v143
	v_mov_b64_e32 v[112:113], s[30:31]
	v_mad_i64_i32 v[120:121], s[20:21], v142, s4, v[112:113]
	v_pk_mul_f32 v[122:123], v[122:123], v[170:171]
	v_pk_mul_f32 v[96:97], v[96:97], v[234:235] op_sel:[0,1]
	v_pk_mul_f32 v[114:115], v[114:115], v[122:123]
	v_pk_mul_f32 v[98:99], v[98:99], v[234:235] op_sel:[0,1]
	v_cvt_pk_bf16_f32 v119, v114, v115
	v_lshlrev_b64 v[114:115], 1, v[164:165]
	v_lshl_add_u64 v[120:121], v[120:121], 0, v[114:115]
	v_subrev_u32_e32 v237, s30, v120
	global_store_dwordx4 v[120:121], v[116:119], off nt
	v_pk_mul_f32 v[102:103], v[102:103], v[234:235] op_sel:[0,1]
	s_nop 0
	v_exp_f32_e32 v116, v108
	v_exp_f32_e32 v117, v109
	v_exp_f32_e32 v118, v110
	v_exp_f32_e32 v119, v111
	v_add_f32_e32 v116, 1.0, v116
	v_add_f32_e32 v117, 1.0, v117
	v_add_f32_e32 v118, 1.0, v118
	v_add_f32_e32 v119, 1.0, v119
	v_rcp_f32_e32 v116, v116
	v_rcp_f32_e32 v117, v117
	v_rcp_f32_e32 v118, v118
	v_rcp_f32_e32 v119, v119
	v_mul_f32_e32 v248, 0xbfb8aa3b, v160
	v_mul_f32_e32 v249, 0xbf317218, v160
	v_pk_mul_f32 v[94:95], v[94:95], v[248:249] op_sel_hi:[1,0]
	v_pk_mul_f32 v[108:109], v[108:109], v[116:117]
	v_pk_mul_f32 v[110:111], v[110:111], v[118:119]
	v_exp_f32_e32 v116, v104
	v_exp_f32_e32 v117, v105
	v_exp_f32_e32 v118, v106
	v_exp_f32_e32 v119, v107
	v_add_f32_e32 v116, 1.0, v116
	v_add_f32_e32 v117, 1.0, v117
	v_add_f32_e32 v118, 1.0, v118
	v_add_f32_e32 v119, 1.0, v119
	v_rcp_f32_e32 v116, v116
	v_rcp_f32_e32 v117, v117
	v_rcp_f32_e32 v118, v118
	v_rcp_f32_e32 v119, v119
	v_pk_mul_f32 v[100:101], v[100:101], v[108:109]
	v_pk_mul_f32 v[104:105], v[104:105], v[116:117]
	v_pk_mul_f32 v[102:103], v[102:103], v[110:111]
	v_pk_mul_f32 v[106:107], v[106:107], v[118:119]
	v_pk_mul_f32 v[92:93], v[92:93], v[248:249] op_sel_hi:[1,0]
	v_pk_mul_f32 v[106:107], v[98:99], v[106:107]
	v_pk_mul_f32 v[98:99], v[96:97], v[104:105]
	v_cvt_pk_bf16_f32 v96, v100, v101
	v_add_u32_e32 v237, 0x16000, v237
	v_cvt_pk_bf16_f32 v97, v102, v103
	v_cvt_pk_bf16_f32 v98, v98, v99
	v_cvt_pk_bf16_f32 v99, v106, v107
	global_store_dwordx4 v237, v[96:99], s[30:31] nt
	v_pk_mul_f32 v[90:91], v[90:91], v[248:249] op_sel_hi:[1,0]
	v_pk_mul_f32 v[88:89], v[88:89], v[248:249] op_sel_hi:[1,0]
	v_exp_f32_e32 v96, v92
	v_exp_f32_e32 v97, v93
	v_exp_f32_e32 v98, v94
	v_exp_f32_e32 v99, v95
	v_add_f32_e32 v96, 1.0, v96
	v_add_f32_e32 v97, 1.0, v97
	v_add_f32_e32 v98, 1.0, v98
	v_add_f32_e32 v99, 1.0, v99
	v_rcp_f32_e32 v96, v96
	v_rcp_f32_e32 v97, v97
	v_rcp_f32_e32 v98, v98
	v_rcp_f32_e32 v99, v99
	ds_bpermute_b32 v158, v147, v146 offset:64
	v_pk_mul_f32 v[92:93], v[92:93], v[96:97]
	v_pk_mul_f32 v[94:95], v[94:95], v[98:99]
	v_exp_f32_e32 v96, v88
	v_exp_f32_e32 v97, v89
	v_exp_f32_e32 v98, v90
	v_exp_f32_e32 v99, v91
	v_add_f32_e32 v96, 1.0, v96
	v_add_f32_e32 v97, 1.0, v97
	v_add_f32_e32 v98, 1.0, v98
	v_add_f32_e32 v99, 1.0, v99
	v_rcp_f32_e32 v96, v96
	v_rcp_f32_e32 v97, v97
	v_rcp_f32_e32 v98, v98
	v_rcp_f32_e32 v99, v99
	v_pk_mul_f32 v[84:85], v[84:85], v[248:249] op_sel:[0,1]
	v_pk_mul_f32 v[88:89], v[88:89], v[96:97]
	v_pk_mul_f32 v[90:91], v[90:91], v[98:99]
	v_pk_mul_f32 v[84:85], v[84:85], v[92:93]
	v_pk_mul_f32 v[80:81], v[80:81], v[248:249] op_sel:[0,1]
	v_pk_mul_f32 v[82:83], v[82:83], v[248:249] op_sel:[0,1]
	v_pk_mul_f32 v[86:87], v[86:87], v[248:249] op_sel:[0,1]
	v_pk_mul_f32 v[90:91], v[82:83], v[90:91]
	v_pk_mul_f32 v[82:83], v[80:81], v[88:89]
	v_cvt_pk_bf16_f32 v80, v84, v85
	v_add_u32_e32 v237, 0x16000, v237
	v_pk_mul_f32 v[86:87], v[86:87], v[94:95]
	v_cvt_pk_bf16_f32 v81, v86, v87
	v_cvt_pk_bf16_f32 v82, v82, v83
	v_cvt_pk_bf16_f32 v83, v90, v91
	s_waitcnt lgkmcnt(0)
; __device__ __forceinline__ f32x4 silu4(f32x4 v) { return (f32x4){silu1(v[0]), silu1(v[1]), silu1(v[2]), silu1(v[3])}; }
; __device__ __forceinline__ u32x4 pack8(f32x4 v0, f32x4 v1) { u32x4 w; w.x = cvt_pk_bf16(v0[0], v0[1]); w.y = cvt_pk_bf16(v0[2], v0[3]); w.z = cvt_pk_bf16(v1[0], v1[1]); w.w = cvt_pk_bf16(v1[2], v1[3]); return w; }
;     __device__ __forceinline__ void operator()(const f32x4 (&acc)[2][2][4][2], const Unit& u, int wr, int wc, int fr, int fq, const Pre& pre) const {
;     ...
; #pragma unroll
;         for (int ai = 0; ai < 2; ++ai)
; #pragma unroll
;             for (int m = 0; m < 4; ++m) { const int row = row0 + ai * HALF + m * 16; const float r = rs8[ai * 4 + m];
;                 const f32x4 g0 = silu4(acc[ai][0][m][0] * r), g1 = silu4(acc[ai][0][m][1] * r);
;                 const f32x4 v0 = g0 * (acc[ai][1][m][0] * r), v1 = g1 * (acc[ai][1][m][1] * r);
;                 *(u32x4*)(O + (size_t)row * 2816 + col0) = pack8(v0, v1); }
	v_mul_f32_e32 v250, 0xbfb8aa3b, v158
	v_mul_f32_e32 v251, 0xbf317218, v158
	v_pk_mul_f32 v[78:79], v[78:79], v[250:251] op_sel_hi:[1,0]
	v_pk_mul_f32 v[76:77], v[76:77], v[250:251] op_sel_hi:[1,0]
	global_store_dwordx4 v237, v[80:83], s[30:31] nt
	v_pk_mul_f32 v[74:75], v[74:75], v[250:251] op_sel_hi:[1,0]
	v_pk_mul_f32 v[72:73], v[72:73], v[250:251] op_sel_hi:[1,0]
	v_exp_f32_e32 v80, v76
	v_exp_f32_e32 v81, v77
	v_exp_f32_e32 v82, v78
	v_exp_f32_e32 v83, v79
	v_add_f32_e32 v80, 1.0, v80
	v_add_f32_e32 v81, 1.0, v81
	v_add_f32_e32 v82, 1.0, v82
	v_add_f32_e32 v83, 1.0, v83
	v_rcp_f32_e32 v80, v80
	v_rcp_f32_e32 v81, v81
	v_rcp_f32_e32 v82, v82
	v_rcp_f32_e32 v83, v83
	v_pk_mul_f32 v[68:69], v[68:69], v[250:251] op_sel:[0,1]
	v_pk_mul_f32 v[76:77], v[76:77], v[80:81]
	v_pk_mul_f32 v[78:79], v[78:79], v[82:83]
	v_exp_f32_e32 v80, v72
	v_exp_f32_e32 v81, v73
	v_exp_f32_e32 v82, v74
	v_exp_f32_e32 v83, v75
	v_add_f32_e32 v80, 1.0, v80
	v_add_f32_e32 v81, 1.0, v81
	v_add_f32_e32 v82, 1.0, v82
	v_add_f32_e32 v83, 1.0, v83
	v_rcp_f32_e32 v80, v80
	v_rcp_f32_e32 v81, v81
	v_rcp_f32_e32 v82, v82
	v_rcp_f32_e32 v83, v83
	v_pk_mul_f32 v[72:73], v[72:73], v[80:81]
	v_pk_mul_f32 v[68:69], v[68:69], v[76:77]
	v_pk_mul_f32 v[74:75], v[74:75], v[82:83]
	v_pk_mul_f32 v[64:65], v[64:65], v[250:251] op_sel:[0,1]
	v_pk_mul_f32 v[66:67], v[66:67], v[250:251] op_sel:[0,1]
	v_pk_mul_f32 v[70:71], v[70:71], v[250:251] op_sel:[0,1]
	v_pk_mul_f32 v[74:75], v[66:67], v[74:75]
	v_pk_mul_f32 v[66:67], v[64:65], v[72:73]
	v_cvt_pk_bf16_f32 v64, v68, v69
	v_add_u32_e32 v237, 0x16000, v237
	v_pk_mul_f32 v[70:71], v[70:71], v[78:79]
	v_cvt_pk_bf16_f32 v65, v70, v71
	v_cvt_pk_bf16_f32 v66, v66, v67
	v_cvt_pk_bf16_f32 v67, v74, v75
	v_mul_f32_e32 v196, 0xbfb8aa3b, v156
	v_mul_f32_e32 v197, 0xbf317218, v156
	v_pk_mul_f32 v[62:63], v[62:63], v[196:197] op_sel_hi:[1,0]
	v_pk_mul_f32 v[60:61], v[60:61], v[196:197] op_sel_hi:[1,0]
	global_store_dwordx4 v237, v[64:67], s[30:31] nt
	v_pk_mul_f32 v[58:59], v[58:59], v[196:197] op_sel_hi:[1,0]
	v_pk_mul_f32 v[56:57], v[56:57], v[196:197] op_sel_hi:[1,0]
	v_exp_f32_e32 v64, v60
	v_exp_f32_e32 v65, v61
	v_exp_f32_e32 v66, v62
	v_exp_f32_e32 v67, v63
	v_add_f32_e32 v64, 1.0, v64
	v_add_f32_e32 v65, 1.0, v65
	v_add_f32_e32 v66, 1.0, v66
	v_add_f32_e32 v67, 1.0, v67
	v_rcp_f32_e32 v64, v64
	v_rcp_f32_e32 v65, v65
	v_rcp_f32_e32 v66, v66
	v_rcp_f32_e32 v67, v67
	ds_bpermute_b32 v154, v147, v146 offset:128
	v_pk_mul_f32 v[60:61], v[60:61], v[64:65]
	v_pk_mul_f32 v[62:63], v[62:63], v[66:67]
	v_exp_f32_e32 v64, v56
	v_exp_f32_e32 v65, v57
	v_exp_f32_e32 v66, v58
	v_exp_f32_e32 v67, v59
	v_add_f32_e32 v64, 1.0, v64
	v_add_f32_e32 v65, 1.0, v65
	v_add_f32_e32 v66, 1.0, v66
	v_add_f32_e32 v67, 1.0, v67
	v_rcp_f32_e32 v64, v64
	v_rcp_f32_e32 v65, v65
	v_rcp_f32_e32 v66, v66
	v_rcp_f32_e32 v67, v67
	v_pk_mul_f32 v[52:53], v[52:53], v[196:197] op_sel:[0,1]
	v_pk_mul_f32 v[56:57], v[56:57], v[64:65]
	v_pk_mul_f32 v[58:59], v[58:59], v[66:67]
	v_pk_mul_f32 v[52:53], v[52:53], v[60:61]
	v_pk_mul_f32 v[48:49], v[48:49], v[196:197] op_sel:[0,1]
	v_pk_mul_f32 v[50:51], v[50:51], v[196:197] op_sel:[0,1]
	v_pk_mul_f32 v[54:55], v[54:55], v[196:197] op_sel:[0,1]
	v_pk_mul_f32 v[58:59], v[50:51], v[58:59]
	v_pk_mul_f32 v[50:51], v[48:49], v[56:57]
	v_cvt_pk_bf16_f32 v48, v52, v53
	v_add_u32_e32 v237, 0x6e000, v237
	v_pk_mul_f32 v[54:55], v[54:55], v[62:63]
	v_cvt_pk_bf16_f32 v49, v54, v55
	v_cvt_pk_bf16_f32 v50, v50, v51
	v_cvt_pk_bf16_f32 v51, v58, v59
	s_waitcnt lgkmcnt(0)
; __device__ __forceinline__ f32x4 silu4(f32x4 v) { return (f32x4){silu1(v[0]), silu1(v[1]), silu1(v[2]), silu1(v[3])}; }
; __device__ __forceinline__ u32x4 pack8(f32x4 v0, f32x4 v1) { u32x4 w; w.x = cvt_pk_bf16(v0[0], v0[1]); w.y = cvt_pk_bf16(v0[2], v0[3]); w.z = cvt_pk_bf16(v1[0], v1[1]); w.w = cvt_pk_bf16(v1[2], v1[3]); return w; }
;     __device__ __forceinline__ void operator()(const f32x4 (&acc)[2][2][4][2], const Unit& u, int wr, int wc, int fr, int fq, const Pre& pre) const {
;     ...
; #pragma unroll
;         for (int ai = 0; ai < 2; ++ai)
; #pragma unroll
;             for (int m = 0; m < 4; ++m) { const int row = row0 + ai * HALF + m * 16; const float r = rs8[ai * 4 + m];
;                 const f32x4 g0 = silu4(acc[ai][0][m][0] * r), g1 = silu4(acc[ai][0][m][1] * r);
;                 const f32x4 v0 = g0 * (acc[ai][1][m][0] * r), v1 = g1 * (acc[ai][1][m][1] * r);
;                 *(u32x4*)(O + (size_t)row * 2816 + col0) = pack8(v0, v1); }
	v_mul_f32_e32 v234, 0xbfb8aa3b, v154
	v_mul_f32_e32 v235, 0xbf317218, v154
	v_pk_mul_f32 v[46:47], v[46:47], v[234:235] op_sel_hi:[1,0]
	v_pk_mul_f32 v[44:45], v[44:45], v[234:235] op_sel_hi:[1,0]
	global_store_dwordx4 v237, v[48:51], s[30:31] nt
	v_pk_mul_f32 v[42:43], v[42:43], v[234:235] op_sel_hi:[1,0]
	v_pk_mul_f32 v[40:41], v[40:41], v[234:235] op_sel_hi:[1,0]
	v_exp_f32_e32 v48, v44
	v_exp_f32_e32 v49, v45
	v_exp_f32_e32 v50, v46
	v_exp_f32_e32 v51, v47
	v_add_f32_e32 v48, 1.0, v48
	v_add_f32_e32 v49, 1.0, v49
	v_add_f32_e32 v50, 1.0, v50
	v_add_f32_e32 v51, 1.0, v51
	v_rcp_f32_e32 v48, v48
	v_rcp_f32_e32 v49, v49
	v_rcp_f32_e32 v50, v50
	v_rcp_f32_e32 v51, v51
	v_pk_mul_f32 v[36:37], v[36:37], v[234:235] op_sel:[0,1]
	v_pk_mul_f32 v[44:45], v[44:45], v[48:49]
	v_pk_mul_f32 v[46:47], v[46:47], v[50:51]
	v_exp_f32_e32 v48, v40
	v_exp_f32_e32 v49, v41
	v_exp_f32_e32 v50, v42
	v_exp_f32_e32 v51, v43
	v_add_f32_e32 v48, 1.0, v48
	v_add_f32_e32 v49, 1.0, v49
	v_add_f32_e32 v50, 1.0, v50
	v_add_f32_e32 v51, 1.0, v51
	v_rcp_f32_e32 v48, v48
	v_rcp_f32_e32 v49, v49
	v_rcp_f32_e32 v50, v50
	v_rcp_f32_e32 v51, v51
	v_pk_mul_f32 v[40:41], v[40:41], v[48:49]
	v_pk_mul_f32 v[36:37], v[36:37], v[44:45]
	v_pk_mul_f32 v[42:43], v[42:43], v[50:51]
	v_pk_mul_f32 v[32:33], v[32:33], v[234:235] op_sel:[0,1]
	v_pk_mul_f32 v[34:35], v[34:35], v[234:235] op_sel:[0,1]
	v_pk_mul_f32 v[38:39], v[38:39], v[234:235] op_sel:[0,1]
	v_pk_mul_f32 v[42:43], v[34:35], v[42:43]
	v_pk_mul_f32 v[34:35], v[32:33], v[40:41]
	v_cvt_pk_bf16_f32 v32, v36, v37
	v_add_u32_e32 v237, 0x16000, v237
	v_pk_mul_f32 v[38:39], v[38:39], v[46:47]
	v_cvt_pk_bf16_f32 v33, v38, v39
	v_cvt_pk_bf16_f32 v34, v34, v35
	v_cvt_pk_bf16_f32 v35, v42, v43
	v_mul_f32_e32 v248, 0xbfb8aa3b, v152
	v_mul_f32_e32 v249, 0xbf317218, v152
	v_pk_mul_f32 v[30:31], v[30:31], v[248:249] op_sel_hi:[1,0]
	v_pk_mul_f32 v[28:29], v[28:29], v[248:249] op_sel_hi:[1,0]
	global_store_dwordx4 v237, v[32:35], s[30:31] nt
	v_pk_mul_f32 v[26:27], v[26:27], v[248:249] op_sel_hi:[1,0]
	v_pk_mul_f32 v[24:25], v[24:25], v[248:249] op_sel_hi:[1,0]
	v_exp_f32_e32 v32, v28
	v_exp_f32_e32 v33, v29
	v_exp_f32_e32 v34, v30
	v_exp_f32_e32 v35, v31
	v_add_f32_e32 v32, 1.0, v32
	v_add_f32_e32 v33, 1.0, v33
	v_add_f32_e32 v34, 1.0, v34
	v_add_f32_e32 v35, 1.0, v35
	v_rcp_f32_e32 v32, v32
	v_rcp_f32_e32 v33, v33
	v_rcp_f32_e32 v34, v34
	v_rcp_f32_e32 v35, v35
	ds_bpermute_b32 v146, v147, v146 offset:192
	v_pk_mul_f32 v[28:29], v[28:29], v[32:33]
	v_pk_mul_f32 v[30:31], v[30:31], v[34:35]
	v_exp_f32_e32 v32, v24
	v_exp_f32_e32 v33, v25
	v_exp_f32_e32 v34, v26
	v_exp_f32_e32 v35, v27
	v_add_f32_e32 v32, 1.0, v32
	v_add_f32_e32 v33, 1.0, v33
	v_add_f32_e32 v34, 1.0, v34
	v_add_f32_e32 v35, 1.0, v35
	v_rcp_f32_e32 v32, v32
	v_rcp_f32_e32 v33, v33
	v_rcp_f32_e32 v34, v34
	v_rcp_f32_e32 v35, v35
	v_pk_mul_f32 v[20:21], v[20:21], v[248:249] op_sel:[0,1]
	v_pk_mul_f32 v[24:25], v[24:25], v[32:33]
	v_pk_mul_f32 v[26:27], v[26:27], v[34:35]
	v_pk_mul_f32 v[20:21], v[20:21], v[28:29]
	v_pk_mul_f32 v[16:17], v[16:17], v[248:249] op_sel:[0,1]
	v_pk_mul_f32 v[18:19], v[18:19], v[248:249] op_sel:[0,1]
	v_pk_mul_f32 v[22:23], v[22:23], v[248:249] op_sel:[0,1]
	v_pk_mul_f32 v[26:27], v[18:19], v[26:27]
	v_pk_mul_f32 v[18:19], v[16:17], v[24:25]
	v_cvt_pk_bf16_f32 v16, v20, v21
	v_add_u32_e32 v237, 0x16000, v237
	v_pk_mul_f32 v[22:23], v[22:23], v[30:31]
	v_cvt_pk_bf16_f32 v17, v22, v23
	v_cvt_pk_bf16_f32 v18, v18, v19
	v_cvt_pk_bf16_f32 v19, v26, v27
	s_waitcnt lgkmcnt(0)
	v_mul_f32_e32 v250, 0xbfb8aa3b, v146
	v_mul_f32_e32 v251, 0xbf317218, v146
	v_pk_mul_f32 v[14:15], v[14:15], v[250:251] op_sel_hi:[1,0]
	v_pk_mul_f32 v[12:13], v[12:13], v[250:251] op_sel_hi:[1,0]
	global_store_dwordx4 v237, v[16:19], s[30:31] nt
	v_pk_mul_f32 v[10:11], v[10:11], v[250:251] op_sel_hi:[1,0]
	v_pk_mul_f32 v[8:9], v[8:9], v[250:251] op_sel_hi:[1,0]
	v_exp_f32_e32 v16, v12
	v_exp_f32_e32 v17, v13
	v_exp_f32_e32 v18, v14
	v_exp_f32_e32 v19, v15
	v_add_f32_e32 v16, 1.0, v16
	v_add_f32_e32 v17, 1.0, v17
	v_add_f32_e32 v18, 1.0, v18
	v_add_f32_e32 v19, 1.0, v19
	v_rcp_f32_e32 v16, v16
	v_rcp_f32_e32 v17, v17
	v_rcp_f32_e32 v18, v18
	v_rcp_f32_e32 v19, v19
	v_pk_mul_f32 v[4:5], v[4:5], v[250:251] op_sel:[0,1]
	v_pk_mul_f32 v[12:13], v[12:13], v[16:17]
	v_pk_mul_f32 v[14:15], v[14:15], v[18:19]
	v_exp_f32_e32 v16, v8
	v_exp_f32_e32 v17, v9
	v_exp_f32_e32 v18, v10
	v_exp_f32_e32 v19, v11
	v_add_f32_e32 v16, 1.0, v16
	v_add_f32_e32 v17, 1.0, v17
	v_add_f32_e32 v18, 1.0, v18
	v_add_f32_e32 v19, 1.0, v19
	v_rcp_f32_e32 v16, v16
	v_rcp_f32_e32 v17, v17
	v_rcp_f32_e32 v18, v18
	v_rcp_f32_e32 v19, v19
	v_pk_mul_f32 v[8:9], v[8:9], v[16:17]
	v_pk_mul_f32 v[4:5], v[4:5], v[12:13]
	v_pk_mul_f32 v[10:11], v[10:11], v[18:19]
	v_pk_mul_f32 v[0:1], v[0:1], v[250:251] op_sel:[0,1]
	v_pk_mul_f32 v[2:3], v[2:3], v[250:251] op_sel:[0,1]
	v_pk_mul_f32 v[6:7], v[6:7], v[250:251] op_sel:[0,1]
	v_pk_mul_f32 v[10:11], v[2:3], v[10:11]
	v_pk_mul_f32 v[2:3], v[0:1], v[8:9]
	v_cvt_pk_bf16_f32 v0, v4, v5
	v_add_u32_e32 v237, 0x16000, v237
	s_mov_b64 s[26:27], -1
	s_andn2_b64 vcc, exec, s[40:41]
	v_pk_mul_f32 v[6:7], v[6:7], v[14:15]
	s_nop 0
	v_cvt_pk_bf16_f32 v1, v6, v7
	v_cvt_pk_bf16_f32 v2, v2, v3
	v_cvt_pk_bf16_f32 v3, v10, v11
	global_store_dwordx4 v237, v[0:3], s[30:31] nt
	s_cbranch_vccnz .LBB0_148
	s_andn2_b64 vcc, exec, s[44:45]
	s_cbranch_vccnz .LBB0_147
	s_barrier
	s_branch .LBB0_147
